# adds: P6 split-K sample tiles: XCD-aware tile-to-workgroup map (4 row blocks x 8 column blocks per XCD) + operand loads in three batches with counted waits
# speedup vs baseline: 1.0150x; 1.0039x over previous
.LBB0_1182:
	s_mov_b32 s32, s14
	s_cmp_lg_u32 s90, 0x100
	s_cbranch_scc1 .Lp6_tilemap_done
	s_and_b32 s32, s14, 1
	s_lshl_b32 s32, s32, 2
	s_bfe_u32 s7, s14, 0x20003
	s_or_b32 s32, s32, s7
	s_lshl_b32 s32, s32, 5
	s_bfe_u32 s7, s14, 0x20001
	s_lshl_b32 s7, s7, 3
	s_or_b32 s32, s32, s7
	s_lshr_b32 s7, s14, 5
	s_or_b32 s32, s32, s7
.Lp6_tilemap_done:
	s_and_b64 vcc, exec, s[0:1]
	s_cbranch_vccz .LBB0_1186
	s_andn2_b64 vcc, exec, s[10:11]
	s_cbranch_vccnz .LBB0_1186
	s_mul_i32 s0, s17, 0x160
	s_mov_b32 s1, 0
	s_lshl_b64 s[2:3], s[0:1], 1
	s_add_u32 s4, s18, s2
	s_addc_u32 s5, s19, s3
	s_add_u32 s2, s24, s2
	s_addc_u32 s3, s25, s3
	s_lshl_b32 s0, s17, 13
	v_lshlrev_b32_e32 v2, 4, v168
	v_mov_b32_e32 v3, 0
	s_add_i32 s0, s0, 0
	v_lshl_add_u64 v[4:5], s[4:5], 0, v[2:3]
	v_lshl_add_u64 v[6:7], s[2:3], 0, v[2:3]
	v_add_u32_e32 v9, s0, v2
	v_and_b32_e32 v2, 0x7e0, v171
	v_lshlrev_b32_e32 v10, 2, v2
	v_and_b32_e32 v2, 28, v171
	v_lshlrev_b32_e32 v8, 7, v1
	v_lshlrev_b32_e32 v11, 2, v2
	v_add3_u32 v18, 0, v10, v11
	s_lshl_b32 s2, s32, 1
	s_lshl_b32 s3, s90, 1
	s_lshl_b32 s4, s32, 5
	s_lshl_b32 s5, s90, 5
	s_movk_i32 s6, 0x1600
	v_add_u32_e32 v19, v9, v8
	v_lshlrev_b32_e32 v8, 1, v2
	v_mov_b32_e32 v9, v3
.LBB0_1185:
	s_and_b32 s7, s2, 0xffffffc0
	s_addk_i32 s7, 0x4000
	v_or_b32_e32 v10, s7, v1
	v_mad_i64_i32 v[12:13], s[10:11], v10, s6, v[4:5]
	v_add_co_u32_e32 v14, vcc, 0x16000, v12
	s_and_b32 s0, s4, 0x3e0
	s_nop 0
	v_addc_co_u32_e32 v15, vcc, 0, v13, vcc
	v_or_b32_e32 v2, s0, v1
	v_add_co_u32_e32 v16, vcc, 0x2c000, v12
	v_mul_u32_u24_e32 v2, 0xb00, v2
	s_nop 0
	v_addc_co_u32_e32 v17, vcc, 0, v13, vcc
	v_lshlrev_b32_e32 v2, 1, v2
	v_add_co_u32_e32 v100, vcc, 0x42000, v12
	v_lshl_add_u64 v[10:11], v[6:7], 0, v[2:3]
	s_nop 0
	v_addc_co_u32_e32 v101, vcc, 0, v13, vcc
	v_add_co_u32_e32 v102, vcc, 0x16000, v10
	v_addc_co_u32_e32 v103, vcc, 0, v11, vcc
	v_mov_b64_e32 v[168:169], v[102:103]
	v_mov_b64_e32 v[252:253], v[100:101]
	global_load_dwordx4 v[20:23], v[10:11], off
	global_load_dwordx4 v[24:27], v[168:169], off
	global_load_dwordx4 v[28:31], v[12:13], off
	global_load_dwordx4 v[32:35], v[14:15], off
	global_load_dwordx4 v[36:39], v[16:17], off
	global_load_dwordx4 v[40:43], v[252:253], off
	global_load_dwordx4 v[44:47], v[10:11], off offset:64
	global_load_dwordx4 v[48:51], v[168:169], off offset:64
	global_load_dwordx4 v[52:55], v[12:13], off offset:64
	global_load_dwordx4 v[56:59], v[14:15], off offset:64
	global_load_dwordx4 v[60:63], v[16:17], off offset:64
	global_load_dwordx4 v[64:67], v[252:253], off offset:64
	global_load_dwordx4 v[68:71], v[10:11], off offset:128
	global_load_dwordx4 v[72:75], v[168:169], off offset:128
	global_load_dwordx4 v[76:79], v[12:13], off offset:128
	global_load_dwordx4 v[80:83], v[14:15], off offset:128
	global_load_dwordx4 v[84:87], v[16:17], off offset:128
	global_load_dwordx4 v[88:91], v[252:253], off offset:128
	global_load_dwordx4 v[92:95], v[10:11], off offset:192
	global_load_dwordx4 v[96:99], v[168:169], off offset:192
	global_load_dwordx4 v[100:103], v[12:13], off offset:192
	global_load_dwordx4 v[104:107], v[14:15], off offset:192
	global_load_dwordx4 v[108:111], v[16:17], off offset:192
	global_load_dwordx4 v[112:115], v[252:253], off offset:192
	global_load_dwordx4 v[172:175], v[10:11], off offset:256
	global_load_dwordx4 v[176:179], v[168:169], off offset:256
	global_load_dwordx4 v[180:183], v[12:13], off offset:256
	global_load_dwordx4 v[184:187], v[14:15], off offset:256
	global_load_dwordx4 v[188:191], v[16:17], off offset:256
	global_load_dwordx4 v[192:195], v[252:253], off offset:256
	global_load_dwordx4 v[196:199], v[10:11], off offset:320
	global_load_dwordx4 v[200:203], v[168:169], off offset:320
	global_load_dwordx4 v[204:207], v[12:13], off offset:320
	global_load_dwordx4 v[208:211], v[14:15], off offset:320
	global_load_dwordx4 v[212:215], v[16:17], off offset:320
	global_load_dwordx4 v[216:219], v[252:253], off offset:320
	global_load_dwordx4 v[220:223], v[10:11], off offset:384
	global_load_dwordx4 v[224:227], v[168:169], off offset:384
	global_load_dwordx4 v[228:231], v[12:13], off offset:384
	global_load_dwordx4 v[232:235], v[14:15], off offset:384
	global_load_dwordx4 v[236:239], v[16:17], off offset:384
	global_load_dwordx4 v[240:243], v[252:253], off offset:384
	s_lshl_b32 s0, s0, 1
	s_add_i32 s14, s14, s90
	s_add_i32 s2, s2, s3
	s_add_i32 s4, s4, s5
	s_cmpk_gt_i32 s14, 0xff
	s_waitcnt vmcnt(36)
	v_mfma_f32_16x16x32_bf16 v[128:131], v[20:23], v[28:31], 0
	v_mfma_f32_16x16x32_bf16 v[132:135], v[20:23], v[32:35], 0
	v_mfma_f32_16x16x32_bf16 v[136:139], v[20:23], v[36:39], 0
	v_mfma_f32_16x16x32_bf16 v[140:143], v[20:23], v[40:43], 0
	v_mfma_f32_16x16x32_bf16 v[144:147], v[24:27], v[28:31], 0
	v_mfma_f32_16x16x32_bf16 v[148:151], v[24:27], v[32:35], 0
	v_mfma_f32_16x16x32_bf16 v[152:155], v[24:27], v[36:39], 0
	v_mfma_f32_16x16x32_bf16 v[156:159], v[24:27], v[40:43], 0
	s_waitcnt vmcnt(30)
	v_mfma_f32_16x16x32_bf16 v[128:131], v[44:47], v[52:55], v[128:131]
	v_mfma_f32_16x16x32_bf16 v[132:135], v[44:47], v[56:59], v[132:135]
	v_mfma_f32_16x16x32_bf16 v[136:139], v[44:47], v[60:63], v[136:139]
	v_mfma_f32_16x16x32_bf16 v[140:143], v[44:47], v[64:67], v[140:143]
	v_mfma_f32_16x16x32_bf16 v[144:147], v[48:51], v[52:55], v[144:147]
	v_mfma_f32_16x16x32_bf16 v[148:151], v[48:51], v[56:59], v[148:151]
	v_mfma_f32_16x16x32_bf16 v[152:155], v[48:51], v[60:63], v[152:155]
	v_mfma_f32_16x16x32_bf16 v[156:159], v[48:51], v[64:67], v[156:159]
	s_waitcnt vmcnt(24)
	v_mfma_f32_16x16x32_bf16 v[128:131], v[68:71], v[76:79], v[128:131]
	v_mfma_f32_16x16x32_bf16 v[132:135], v[68:71], v[80:83], v[132:135]
	v_mfma_f32_16x16x32_bf16 v[136:139], v[68:71], v[84:87], v[136:139]
	v_mfma_f32_16x16x32_bf16 v[140:143], v[68:71], v[88:91], v[140:143]
	v_mfma_f32_16x16x32_bf16 v[144:147], v[72:75], v[76:79], v[144:147]
	v_mfma_f32_16x16x32_bf16 v[148:151], v[72:75], v[80:83], v[148:151]
	v_mfma_f32_16x16x32_bf16 v[152:155], v[72:75], v[84:87], v[152:155]
	v_mfma_f32_16x16x32_bf16 v[156:159], v[72:75], v[88:91], v[156:159]
	s_waitcnt vmcnt(18)
	v_mfma_f32_16x16x32_bf16 v[128:131], v[92:95], v[100:103], v[128:131]
	v_mfma_f32_16x16x32_bf16 v[132:135], v[92:95], v[104:107], v[132:135]
	v_mfma_f32_16x16x32_bf16 v[136:139], v[92:95], v[108:111], v[136:139]
	v_mfma_f32_16x16x32_bf16 v[140:143], v[92:95], v[112:115], v[140:143]
	v_mfma_f32_16x16x32_bf16 v[144:147], v[96:99], v[100:103], v[144:147]
	v_mfma_f32_16x16x32_bf16 v[148:151], v[96:99], v[104:107], v[148:151]
	v_mfma_f32_16x16x32_bf16 v[152:155], v[96:99], v[108:111], v[152:155]
	v_mfma_f32_16x16x32_bf16 v[156:159], v[96:99], v[112:115], v[156:159]
	global_load_dwordx4 v[20:23], v[10:11], off offset:448
	global_load_dwordx4 v[24:27], v[168:169], off offset:448
	global_load_dwordx4 v[28:31], v[12:13], off offset:448
	global_load_dwordx4 v[32:35], v[14:15], off offset:448
	global_load_dwordx4 v[36:39], v[16:17], off offset:448
	global_load_dwordx4 v[40:43], v[252:253], off offset:448
	global_load_dwordx4 v[44:47], v[10:11], off offset:512
	global_load_dwordx4 v[48:51], v[168:169], off offset:512
	global_load_dwordx4 v[52:55], v[12:13], off offset:512
	global_load_dwordx4 v[56:59], v[14:15], off offset:512
	global_load_dwordx4 v[60:63], v[16:17], off offset:512
	global_load_dwordx4 v[64:67], v[252:253], off offset:512
	global_load_dwordx4 v[68:71], v[10:11], off offset:576
	global_load_dwordx4 v[72:75], v[168:169], off offset:576
	global_load_dwordx4 v[76:79], v[12:13], off offset:576
	global_load_dwordx4 v[80:83], v[14:15], off offset:576
	global_load_dwordx4 v[84:87], v[16:17], off offset:576
	global_load_dwordx4 v[88:91], v[252:253], off offset:576
	global_load_dwordx4 v[92:95], v[10:11], off offset:640
	global_load_dwordx4 v[96:99], v[168:169], off offset:640
	global_load_dwordx4 v[100:103], v[12:13], off offset:640
	global_load_dwordx4 v[104:107], v[14:15], off offset:640
	global_load_dwordx4 v[108:111], v[16:17], off offset:640
	global_load_dwordx4 v[112:115], v[252:253], off offset:640
	s_waitcnt vmcnt(36)
	v_mfma_f32_16x16x32_bf16 v[128:131], v[172:175], v[180:183], v[128:131]
	v_mfma_f32_16x16x32_bf16 v[132:135], v[172:175], v[184:187], v[132:135]
	v_mfma_f32_16x16x32_bf16 v[136:139], v[172:175], v[188:191], v[136:139]
	v_mfma_f32_16x16x32_bf16 v[140:143], v[172:175], v[192:195], v[140:143]
	v_mfma_f32_16x16x32_bf16 v[144:147], v[176:179], v[180:183], v[144:147]
	v_mfma_f32_16x16x32_bf16 v[148:151], v[176:179], v[184:187], v[148:151]
	v_mfma_f32_16x16x32_bf16 v[152:155], v[176:179], v[188:191], v[152:155]
	v_mfma_f32_16x16x32_bf16 v[156:159], v[176:179], v[192:195], v[156:159]
	s_waitcnt vmcnt(30)
	v_mfma_f32_16x16x32_bf16 v[128:131], v[196:199], v[204:207], v[128:131]
	v_mfma_f32_16x16x32_bf16 v[132:135], v[196:199], v[208:211], v[132:135]
	v_mfma_f32_16x16x32_bf16 v[136:139], v[196:199], v[212:215], v[136:139]
	v_mfma_f32_16x16x32_bf16 v[140:143], v[196:199], v[216:219], v[140:143]
	v_mfma_f32_16x16x32_bf16 v[144:147], v[200:203], v[204:207], v[144:147]
	v_mfma_f32_16x16x32_bf16 v[148:151], v[200:203], v[208:211], v[148:151]
	v_mfma_f32_16x16x32_bf16 v[152:155], v[200:203], v[212:215], v[152:155]
	v_mfma_f32_16x16x32_bf16 v[156:159], v[200:203], v[216:219], v[156:159]
	s_waitcnt vmcnt(24)
	v_mfma_f32_16x16x32_bf16 v[128:131], v[220:223], v[228:231], v[128:131]
	v_mfma_f32_16x16x32_bf16 v[132:135], v[220:223], v[232:235], v[132:135]
	v_mfma_f32_16x16x32_bf16 v[136:139], v[220:223], v[236:239], v[136:139]
	v_mfma_f32_16x16x32_bf16 v[140:143], v[220:223], v[240:243], v[140:143]
	v_mfma_f32_16x16x32_bf16 v[144:147], v[224:227], v[228:231], v[144:147]
	v_mfma_f32_16x16x32_bf16 v[148:151], v[224:227], v[232:235], v[148:151]
	v_mfma_f32_16x16x32_bf16 v[152:155], v[224:227], v[236:239], v[152:155]
	v_mfma_f32_16x16x32_bf16 v[156:159], v[224:227], v[240:243], v[156:159]
	s_waitcnt vmcnt(18)
	v_mfma_f32_16x16x32_bf16 v[128:131], v[20:23], v[28:31], v[128:131]
	v_mfma_f32_16x16x32_bf16 v[132:135], v[20:23], v[32:35], v[132:135]
	v_mfma_f32_16x16x32_bf16 v[136:139], v[20:23], v[36:39], v[136:139]
	v_mfma_f32_16x16x32_bf16 v[140:143], v[20:23], v[40:43], v[140:143]
	v_mfma_f32_16x16x32_bf16 v[144:147], v[24:27], v[28:31], v[144:147]
	v_mfma_f32_16x16x32_bf16 v[148:151], v[24:27], v[32:35], v[148:151]
	v_mfma_f32_16x16x32_bf16 v[152:155], v[24:27], v[36:39], v[152:155]
	v_mfma_f32_16x16x32_bf16 v[156:159], v[24:27], v[40:43], v[156:159]
	s_waitcnt vmcnt(12)
	v_mfma_f32_16x16x32_bf16 v[128:131], v[44:47], v[52:55], v[128:131]
	v_mfma_f32_16x16x32_bf16 v[132:135], v[44:47], v[56:59], v[132:135]
	v_mfma_f32_16x16x32_bf16 v[136:139], v[44:47], v[60:63], v[136:139]
	v_mfma_f32_16x16x32_bf16 v[140:143], v[44:47], v[64:67], v[140:143]
	v_mfma_f32_16x16x32_bf16 v[144:147], v[48:51], v[52:55], v[144:147]
	v_mfma_f32_16x16x32_bf16 v[148:151], v[48:51], v[56:59], v[148:151]
	v_mfma_f32_16x16x32_bf16 v[152:155], v[48:51], v[60:63], v[152:155]
	v_mfma_f32_16x16x32_bf16 v[156:159], v[48:51], v[64:67], v[156:159]
	s_waitcnt vmcnt(6)
	v_mfma_f32_16x16x32_bf16 v[128:131], v[68:71], v[76:79], v[128:131]
	v_mfma_f32_16x16x32_bf16 v[132:135], v[68:71], v[80:83], v[132:135]
	v_mfma_f32_16x16x32_bf16 v[136:139], v[68:71], v[84:87], v[136:139]
	v_mfma_f32_16x16x32_bf16 v[140:143], v[68:71], v[88:91], v[140:143]
	v_mfma_f32_16x16x32_bf16 v[144:147], v[72:75], v[76:79], v[144:147]
	v_mfma_f32_16x16x32_bf16 v[148:151], v[72:75], v[80:83], v[148:151]
	v_mfma_f32_16x16x32_bf16 v[152:155], v[72:75], v[84:87], v[152:155]
	v_mfma_f32_16x16x32_bf16 v[156:159], v[72:75], v[88:91], v[156:159]
	s_waitcnt vmcnt(0)
	v_mfma_f32_16x16x32_bf16 v[128:131], v[92:95], v[100:103], v[128:131]
	v_mfma_f32_16x16x32_bf16 v[132:135], v[92:95], v[104:107], v[132:135]
	v_mfma_f32_16x16x32_bf16 v[136:139], v[92:95], v[108:111], v[136:139]
	v_mfma_f32_16x16x32_bf16 v[140:143], v[92:95], v[112:115], v[140:143]
	v_mfma_f32_16x16x32_bf16 v[144:147], v[96:99], v[100:103], v[144:147]
	v_mfma_f32_16x16x32_bf16 v[148:151], v[96:99], v[104:107], v[148:151]
	v_mfma_f32_16x16x32_bf16 v[152:155], v[96:99], v[108:111], v[152:155]
	v_mfma_f32_16x16x32_bf16 v[156:159], v[96:99], v[112:115], v[156:159]
	v_or_b32_e32 v244, s7, v170
	v_ashrrev_i32_e32 v245, 31, v244
	v_lshlrev_b64 v[244:245], 11, v[244:245]
	v_lshl_add_u64 v[244:245], s[8:9], 0, v[244:245]
	v_lshl_add_u64 v[244:245], v[244:245], 0, s[0:1]
	v_lshl_add_u64 v[56:57], v[244:245], 0, v[8:9]
	s_waitcnt lgkmcnt(0)
	s_barrier
	s_nop 7
	s_nop 7
	ds_write_b128 v19, v[128:131]
	ds_write_b128 v19, v[132:135] offset:2048
	ds_write_b128 v19, v[136:139] offset:4096
	ds_write_b128 v19, v[140:143] offset:6144
	ds_write_b128 v19, v[144:147] offset:64
	ds_write_b128 v19, v[148:151] offset:2112
	ds_write_b128 v19, v[152:155] offset:4160
	ds_write_b128 v19, v[156:159] offset:6208
	s_waitcnt lgkmcnt(0)
	s_barrier
	global_load_dwordx2 v[44:45], v[56:57], off
	ds_read_b128 v[10:13], v18
	ds_read_b128 v[14:17], v18 offset:8192
	ds_read_b128 v[20:23], v18 offset:16384
	ds_read_b128 v[24:27], v18 offset:24576
	ds_read_b128 v[28:31], v18 offset:32768
	ds_read_b128 v[32:35], v18 offset:40960
	ds_read_b128 v[36:39], v18 offset:49152
	ds_read_b128 v[40:43], v18 offset:57344
	s_waitcnt lgkmcnt(7)
	v_pk_add_f32 v[12:13], v[12:13], 0 op_sel_hi:[1,0]
	v_pk_add_f32 v[10:11], v[10:11], 0 op_sel_hi:[1,0]
	s_waitcnt lgkmcnt(6)
	v_pk_add_f32 v[12:13], v[12:13], v[16:17]
	v_pk_add_f32 v[10:11], v[10:11], v[14:15]
	s_waitcnt lgkmcnt(5)
	v_pk_add_f32 v[12:13], v[12:13], v[22:23]
	v_pk_add_f32 v[10:11], v[10:11], v[20:21]
	s_waitcnt lgkmcnt(4)
	v_pk_add_f32 v[12:13], v[12:13], v[26:27]
	v_pk_add_f32 v[10:11], v[10:11], v[24:25]
	s_waitcnt lgkmcnt(3)
	v_pk_add_f32 v[12:13], v[12:13], v[30:31]
	v_pk_add_f32 v[10:11], v[10:11], v[28:29]
	s_waitcnt lgkmcnt(2)
	v_pk_add_f32 v[12:13], v[12:13], v[34:35]
	v_pk_add_f32 v[10:11], v[10:11], v[32:33]
	s_waitcnt lgkmcnt(1)
	v_pk_add_f32 v[12:13], v[12:13], v[38:39]
	v_pk_add_f32 v[10:11], v[10:11], v[36:37]
	s_waitcnt lgkmcnt(0)
	v_pk_add_f32 v[12:13], v[12:13], v[42:43]
	v_pk_add_f32 v[10:11], v[10:11], v[40:41]
	s_waitcnt vmcnt(0)
	v_lshlrev_b32_e32 v2, 16, v44
	v_and_b32_e32 v14, 0xffff0000, v44
	v_lshlrev_b32_e32 v15, 16, v45
	v_and_b32_e32 v16, 0xffff0000, v45
	v_add_f32_e32 v2, v10, v2
	v_add_f32_e32 v10, v11, v14
	v_add_f32_e32 v11, v12, v15
	v_add_f32_e32 v12, v13, v16
	v_cvt_pk_bf16_f32 v10, v2, v10
	v_cvt_pk_bf16_f32 v11, v11, v12
	global_store_dwordx2 v[56:57], v[10:11], off sc1
	s_cbranch_scc0 .LBB0_1185
.LBB0_1186:
	s_waitcnt vmcnt(0)
	s_waitcnt lgkmcnt(0)
	s_barrier
	s_mov_b64 s[0:1], exec
	v_readlane_b32 s2, v254, 2
	v_readlane_b32 s3, v254, 3
	s_and_b64 s[2:3], s[0:1], s[2:3]
	s_mov_b64 exec, s[2:3]
	s_cbranch_execz .LBB0_1238
	s_cmp_lg_u32 s90, 0x100
	s_cbranch_scc1 .Lfl10_full
	s_and_b32 s20, s14, 0xff
	s_lshr_b32 s2, s32, 5
	s_lshl_b32 s2, s2, 6
	s_add_i32 s2, s2, 0x3800
	s_add_u32 s2, s74, s2
	s_addc_u32 s3, s75, 0
	v_mov_b32_e32 v2, 0
	v_mov_b32_e32 v3, 1
	s_waitcnt vmcnt(0)
	global_atomic_add v2, v3, s[2:3]
	s_cmp_gt_u32 s20, 63
	s_cbranch_scc1 .LBB0_1238
	s_lshr_b32 s4, s20, 3
	s_lshl_b32 s4, s4, 6
	s_add_i32 s4, s4, 0x3800
	s_add_u32 s4, s74, s4
	s_addc_u32 s5, s75, 0
	s_mov_b32 s22, 0
